# LDS-DMA groups issued before ds_reads within each load segment of the P5/P7 K-loops; + conv de-serialised, swapped-V, nop drop, preamble burst
# speedup vs baseline: 1.0107x; 1.0024x over previous
; #define PG8_STAGE(bufoff, gbase, voff) do { _Pragma("unroll") for (int _i = 0; _i < 2; ++_i) \
;         __builtin_amdgcn_global_load_lds((const unsigned*)((const char*)(gbase) + (voff)[_i]), (PG8_LAS unsigned*)(lds + (bufoff) + ldsw + _i * 8192), 16, 0, 0); } while (0)
; #define PG8_LDA(dst, b, h) do { _Pragma("unroll") for (int m = 0; m < 4; ++m) _Pragma("unroll") for (int k = 0; k < 2; ++k) dst[m][k] = *(const PG8_LAS bf16x8*)(lds + PG8_SA(b, h) + aoff + m * 2048 + k * 1024); } while (0)
; #define PG8_LDB(dst, b, h) do { _Pragma("unroll") for (int n = 0; n < 2; ++n) _Pragma("unroll") for (int k = 0; k < 2; ++k) dst[n][k] = *(const PG8_LAS bf16x8*)(lds + PG8_SB(b, h) + boff + n * 2048 + k * 1024); } while (0)
; #define PG8_MMA(ai, bj, At, Bt) do { __builtin_amdgcn_s_setprio(1); _Pragma("unroll") for (int m = 0; m < 4; ++m) _Pragma("unroll") for (int n = 0; n < 2; ++n) _Pragma("unroll") for (int k = 0; k < 2; ++k) \
;         acc[ai][bj][m][n] = __builtin_amdgcn_mfma_f32_16x16x32_bf16(Bt[n][k], At[m][k], acc[ai][bj][m][n], 0, 0, 0); __builtin_amdgcn_s_setprio(0); } while (0)
; #define PG8_WAIT_V(n) asm volatile("s_waitcnt vmcnt(" #n ")" ::: "memory")
; template <class Epi, class Sched, bool ALIGN_EPI = false, bool SP2 = false>
; __device__ __forceinline__ void gemm_phase(PG8_LAS unsigned char* lds, const Gemm g, const Sched& S, const Epi& E) {
;     ...
;             PG8_LDB(B0, 0, 0); PG8_LDB(B1, 0, 1); PG8_SCHED; PG8_LDA(At, 0, 0); PG8_STAGE(PG8_SA(1, 1), a1 + hstep, voffA);
;             PG8_WAIT_V(8); PG8_WAIT_L(0); PG8_BAR; PG8_MMA(0, 0, At, B0); PG8_MMA(0, 1, At, B1); PG8_BAR; PG8_SCHED;
;             PG8_LDA(At, 0, 1); PG8_STAGE(PG8_SB(0, 0), b2, voffB); PG8_STAGE(PG8_SB(0, 1), b2 + hstep, voffB); PG8_STAGE(PG8_SA(0, 0), a2, voffA);
;             PG8_WAIT_V(8); PG8_WAIT_L(0); PG8_BAR; PG8_MMA(1, 0, At, B0); PG8_MMA(1, 1, At, B1); PG8_BAR; PG8_SCHED;
;             PG8_LDB(B0, 1, 0); PG8_LDB(B1, 1, 1); PG8_SCHED; PG8_LDA(At, 1, 0); PG8_STAGE(PG8_SA(0, 1), a2 + hstep, voffA);
;             PG8_WAIT_V(8); PG8_WAIT_L(0); PG8_BAR; PG8_MMA(0, 0, At, B0); PG8_MMA(0, 1, At, B1); PG8_BAR; PG8_SCHED;
;             PG8_LDA(At, 1, 1); PG8_STAGE(PG8_SB(1, 0), b3, voffB); PG8_STAGE(PG8_SB(1, 1), b3 + hstep, voffB); PG8_STAGE(PG8_SA(1, 0), a3, voffA);
;             PG8_WAIT_V(8); PG8_WAIT_L(0); PG8_BAR; PG8_MMA(1, 0, At, B0); PG8_MMA(1, 1, At, B1); PG8_BAR; PG8_SCHED;
.LBB0_574:
	s_add_u32 s0, s10, 0xfffc0080
	s_addc_u32 s1, s11, -1
	s_cmp_eq_u32 s21, 12
	s_cselect_b32 s15, s65, s1
	s_cselect_b32 s14, s64, s0
	s_cselect_b32 s13, s16, s20
	s_cselect_b32 s12, s17, s19
	v_lshl_add_u64 v[214:215], s[10:11], 0, v[186:187]
	s_add_i32 m0, s69, 0xc000
	s_nop 0
	global_load_lds_dwordx4 v[214:215], off
	v_lshl_add_u64 v[214:215], s[10:11], 0, v[188:189]
	s_add_i32 m0, s69, 0xe000
	s_nop 0
	global_load_lds_dwordx4 v[214:215], off
	ds_read_b128 v[128:131], v224
	ds_read_b128 v[132:135], v224 offset:1024
	ds_read_b128 v[136:139], v224 offset:2048
	ds_read_b128 v[140:143], v224 offset:3072
	ds_read_b128 v[144:147], v225
	ds_read_b128 v[148:151], v225 offset:1024
	ds_read_b128 v[152:155], v225 offset:2048
	ds_read_b128 v[156:159], v225 offset:3072
	ds_read_b128 v[160:163], v226
	ds_read_b128 v[164:167], v226 offset:1024
	ds_read_b128 v[168:171], v226 offset:2048
	ds_read_b128 v[172:175], v226 offset:3072
	ds_read_b128 v[196:199], v226 offset:4096
	ds_read_b128 v[200:203], v226 offset:5120
	ds_read_b128 v[204:207], v226 offset:6144
	ds_read_b128 v[210:213], v226 offset:7168
	s_waitcnt vmcnt(8)
	s_waitcnt lgkmcnt(0)
	s_barrier
	s_setprio 1
	s_waitcnt lgkmcnt(0)
	v_mfma_f32_16x16x32_bf16 v[92:95], v[128:131], v[160:163], v[92:95]
	v_mfma_f32_16x16x32_bf16 v[44:47], v[136:139], v[160:163], v[44:47]
	v_mfma_f32_16x16x32_bf16 v[84:87], v[128:131], v[168:171], v[84:87]
	v_mfma_f32_16x16x32_bf16 v[36:39], v[136:139], v[168:171], v[36:39]
	v_mfma_f32_16x16x32_bf16 v[76:79], v[128:131], v[196:199], v[76:79]
	v_mfma_f32_16x16x32_bf16 v[28:31], v[136:139], v[196:199], v[28:31]
	v_mfma_f32_16x16x32_bf16 v[124:127], v[128:131], v[204:207], v[124:127]
	v_mfma_f32_16x16x32_bf16 v[120:123], v[136:139], v[204:207], v[120:123]
	v_mfma_f32_16x16x32_bf16 v[92:95], v[132:135], v[164:167], v[92:95]
	v_mfma_f32_16x16x32_bf16 v[44:47], v[140:143], v[164:167], v[44:47]
	v_mfma_f32_16x16x32_bf16 v[84:87], v[132:135], v[172:175], v[84:87]
	v_mfma_f32_16x16x32_bf16 v[36:39], v[140:143], v[172:175], v[36:39]
	v_mfma_f32_16x16x32_bf16 v[76:79], v[132:135], v[200:203], v[76:79]
	v_mfma_f32_16x16x32_bf16 v[28:31], v[140:143], v[200:203], v[28:31]
	v_mfma_f32_16x16x32_bf16 v[124:127], v[132:135], v[210:213], v[124:127]
	v_mfma_f32_16x16x32_bf16 v[120:123], v[140:143], v[210:213], v[120:123]
	s_setprio 0
	s_setprio 1
	v_mfma_f32_16x16x32_bf16 v[88:91], v[144:147], v[160:163], v[88:91]
	v_mfma_f32_16x16x32_bf16 v[40:43], v[152:155], v[160:163], v[40:43]
	v_mfma_f32_16x16x32_bf16 v[80:83], v[144:147], v[168:171], v[80:83]
	v_mfma_f32_16x16x32_bf16 v[32:35], v[152:155], v[168:171], v[32:35]
	v_mfma_f32_16x16x32_bf16 v[72:75], v[144:147], v[196:199], v[72:75]
	v_mfma_f32_16x16x32_bf16 v[24:27], v[152:155], v[196:199], v[24:27]
	v_mfma_f32_16x16x32_bf16 v[116:119], v[144:147], v[204:207], v[116:119]
	v_mfma_f32_16x16x32_bf16 v[112:115], v[152:155], v[204:207], v[112:115]
	v_mfma_f32_16x16x32_bf16 v[88:91], v[148:151], v[164:167], v[88:91]
	v_mfma_f32_16x16x32_bf16 v[40:43], v[156:159], v[164:167], v[40:43]
	v_mfma_f32_16x16x32_bf16 v[80:83], v[148:151], v[172:175], v[80:83]
	v_mfma_f32_16x16x32_bf16 v[32:35], v[156:159], v[172:175], v[32:35]
	v_mfma_f32_16x16x32_bf16 v[72:75], v[148:151], v[200:203], v[72:75]
	v_mfma_f32_16x16x32_bf16 v[24:27], v[156:159], v[200:203], v[24:27]
	v_mfma_f32_16x16x32_bf16 v[116:119], v[148:151], v[210:213], v[116:119]
	v_mfma_f32_16x16x32_bf16 v[112:115], v[156:159], v[210:213], v[112:115]
	s_setprio 0
	s_barrier
	s_add_i32 s0, s97, s75
	v_lshl_add_u64 v[214:215], s[12:13], 0, v[178:179]
	s_mov_b32 m0, s0
	s_nop 0
	global_load_lds_dwordx4 v[214:215], off
	s_add_i32 m0, s0, 0x2000
	s_add_u32 s22, s12, 0x40000
	v_lshl_add_u64 v[216:217], s[12:13], 0, v[182:183]
	s_addc_u32 s23, s13, 0
	s_add_i32 s0, s72, s75
	global_load_lds_dwordx4 v[216:217], off
	v_lshl_add_u64 v[218:219], s[22:23], 0, v[178:179]
	s_mov_b32 m0, s0
	v_lshl_add_u64 v[220:221], s[14:15], 0, v[180:181]
	global_load_lds_dwordx4 v[218:219], off
	v_lshl_add_u64 v[218:219], s[22:23], 0, v[182:183]
	s_add_i32 m0, s0, 0x2000
	s_nop 0
	global_load_lds_dwordx4 v[218:219], off
	v_lshl_add_u64 v[218:219], s[14:15], 0, v[176:177]
	s_mov_b32 m0, s69
	s_nop 0
	global_load_lds_dwordx4 v[218:219], off
	s_mov_b32 m0, s76
	s_nop 0
	global_load_lds_dwordx4 v[220:221], off
	ds_read_b128 v[160:163], v226 offset:16384
	ds_read_b128 v[164:167], v226 offset:17408
	ds_read_b128 v[168:171], v226 offset:18432
	ds_read_b128 v[172:175], v226 offset:19456
	ds_read_b128 v[196:199], v226 offset:20480
	ds_read_b128 v[200:203], v226 offset:21504
	ds_read_b128 v[204:207], v226 offset:22528
	ds_read_b128 v[210:213], v226 offset:23552
	s_waitcnt vmcnt(8)
	s_waitcnt lgkmcnt(0)
	s_barrier
; #define PG8_STAGE(bufoff, gbase, voff) do { _Pragma("unroll") for (int _i = 0; _i < 2; ++_i) \
;         __builtin_amdgcn_global_load_lds((const unsigned*)((const char*)(gbase) + (voff)[_i]), (PG8_LAS unsigned*)(lds + (bufoff) + ldsw + _i * 8192), 16, 0, 0); } while (0)
; #define PG8_LDA(dst, b, h) do { _Pragma("unroll") for (int m = 0; m < 4; ++m) _Pragma("unroll") for (int k = 0; k < 2; ++k) dst[m][k] = *(const PG8_LAS bf16x8*)(lds + PG8_SA(b, h) + aoff + m * 2048 + k * 1024); } while (0)
; #define PG8_LDB(dst, b, h) do { _Pragma("unroll") for (int n = 0; n < 2; ++n) _Pragma("unroll") for (int k = 0; k < 2; ++k) dst[n][k] = *(const PG8_LAS bf16x8*)(lds + PG8_SB(b, h) + boff + n * 2048 + k * 1024); } while (0)
; #define PG8_MMA(ai, bj, At, Bt) do { __builtin_amdgcn_s_setprio(1); _Pragma("unroll") for (int m = 0; m < 4; ++m) _Pragma("unroll") for (int n = 0; n < 2; ++n) _Pragma("unroll") for (int k = 0; k < 2; ++k) \
;         acc[ai][bj][m][n] = __builtin_amdgcn_mfma_f32_16x16x32_bf16(Bt[n][k], At[m][k], acc[ai][bj][m][n], 0, 0, 0); __builtin_amdgcn_s_setprio(0); } while (0)
; #define PG8_WAIT_V(n) asm volatile("s_waitcnt vmcnt(" #n ")" ::: "memory")
; template <class Epi, class Sched, bool ALIGN_EPI = false, bool SP2 = false>
; __device__ __forceinline__ void gemm_phase(PG8_LAS unsigned char* lds, const Gemm g, const Sched& S, const Epi& E) {
;     ...
;             PG8_LDB(B0, 0, 0); PG8_LDB(B1, 0, 1); PG8_SCHED; PG8_LDA(At, 0, 0); PG8_STAGE(PG8_SA(1, 1), a1 + hstep, voffA);
;             PG8_WAIT_V(8); PG8_WAIT_L(0); PG8_BAR; PG8_MMA(0, 0, At, B0); PG8_MMA(0, 1, At, B1); PG8_BAR; PG8_SCHED;
;             PG8_LDA(At, 0, 1); PG8_STAGE(PG8_SB(0, 0), b2, voffB); PG8_STAGE(PG8_SB(0, 1), b2 + hstep, voffB); PG8_STAGE(PG8_SA(0, 0), a2, voffA);
;             PG8_WAIT_V(8); PG8_WAIT_L(0); PG8_BAR; PG8_MMA(1, 0, At, B0); PG8_MMA(1, 1, At, B1); PG8_BAR; PG8_SCHED;
;             PG8_LDB(B0, 1, 0); PG8_LDB(B1, 1, 1); PG8_SCHED; PG8_LDA(At, 1, 0); PG8_STAGE(PG8_SA(0, 1), a2 + hstep, voffA);
;             PG8_WAIT_V(8); PG8_WAIT_L(0); PG8_BAR; PG8_MMA(0, 0, At, B0); PG8_MMA(0, 1, At, B1); PG8_BAR; PG8_SCHED;
;             PG8_LDA(At, 1, 1); PG8_STAGE(PG8_SB(1, 0), b3, voffB); PG8_STAGE(PG8_SB(1, 1), b3 + hstep, voffB); PG8_STAGE(PG8_SA(1, 0), a3, voffA);
;             PG8_WAIT_V(8); PG8_WAIT_L(0); PG8_BAR; PG8_MMA(1, 0, At, B0); PG8_MMA(1, 1, At, B1); PG8_BAR; PG8_SCHED;
	s_setprio 1
	s_waitcnt lgkmcnt(0)
	v_mfma_f32_16x16x32_bf16 v[68:71], v[128:131], v[160:163], v[68:71]
	v_mfma_f32_16x16x32_bf16 v[20:23], v[136:139], v[160:163], v[20:23]
	v_mfma_f32_16x16x32_bf16 v[60:63], v[128:131], v[168:171], v[60:63]
	v_mfma_f32_16x16x32_bf16 v[12:15], v[136:139], v[168:171], v[12:15]
	v_mfma_f32_16x16x32_bf16 v[52:55], v[128:131], v[196:199], v[52:55]
	v_mfma_f32_16x16x32_bf16 v[4:7], v[136:139], v[196:199], v[4:7]
	v_mfma_f32_16x16x32_bf16 v[108:111], v[128:131], v[204:207], v[108:111]
	v_mfma_f32_16x16x32_bf16 v[104:107], v[136:139], v[204:207], v[104:107]
	v_mfma_f32_16x16x32_bf16 v[68:71], v[132:135], v[164:167], v[68:71]
	v_mfma_f32_16x16x32_bf16 v[20:23], v[140:143], v[164:167], v[20:23]
	v_mfma_f32_16x16x32_bf16 v[60:63], v[132:135], v[172:175], v[60:63]
	v_mfma_f32_16x16x32_bf16 v[12:15], v[140:143], v[172:175], v[12:15]
	v_mfma_f32_16x16x32_bf16 v[52:55], v[132:135], v[200:203], v[52:55]
	v_mfma_f32_16x16x32_bf16 v[4:7], v[140:143], v[200:203], v[4:7]
	v_mfma_f32_16x16x32_bf16 v[108:111], v[132:135], v[210:213], v[108:111]
	v_mfma_f32_16x16x32_bf16 v[104:107], v[140:143], v[210:213], v[104:107]
	s_setprio 0
	s_setprio 1
	v_mfma_f32_16x16x32_bf16 v[64:67], v[144:147], v[160:163], v[64:67]
	v_mfma_f32_16x16x32_bf16 v[16:19], v[152:155], v[160:163], v[16:19]
	v_mfma_f32_16x16x32_bf16 v[56:59], v[144:147], v[168:171], v[56:59]
	v_mfma_f32_16x16x32_bf16 v[8:11], v[152:155], v[168:171], v[8:11]
	v_mfma_f32_16x16x32_bf16 v[48:51], v[144:147], v[196:199], v[48:51]
	v_mfma_f32_16x16x32_bf16 v[0:3], v[152:155], v[196:199], v[0:3]
	v_mfma_f32_16x16x32_bf16 v[100:103], v[144:147], v[204:207], v[100:103]
	v_mfma_f32_16x16x32_bf16 v[96:99], v[152:155], v[204:207], v[96:99]
	v_mfma_f32_16x16x32_bf16 v[64:67], v[148:151], v[164:167], v[64:67]
	v_mfma_f32_16x16x32_bf16 v[16:19], v[156:159], v[164:167], v[16:19]
	v_mfma_f32_16x16x32_bf16 v[56:59], v[148:151], v[172:175], v[56:59]
	v_mfma_f32_16x16x32_bf16 v[8:11], v[156:159], v[172:175], v[8:11]
	v_mfma_f32_16x16x32_bf16 v[48:51], v[148:151], v[200:203], v[48:51]
	v_mfma_f32_16x16x32_bf16 v[0:3], v[156:159], v[200:203], v[0:3]
	v_mfma_f32_16x16x32_bf16 v[100:103], v[148:151], v[210:213], v[100:103]
	v_mfma_f32_16x16x32_bf16 v[96:99], v[156:159], v[210:213], v[96:99]
	s_setprio 0
	s_barrier
	s_add_u32 s14, s14, 0x40000
	s_addc_u32 s15, s15, 0
	s_mov_b32 m0, s77
	v_lshl_add_u64 v[228:229], s[14:15], 0, v[176:177]
	global_load_lds_dwordx4 v[228:229], off
	v_lshl_add_u64 v[228:229], s[14:15], 0, v[180:181]
	s_mov_b32 m0, s78
	s_nop 0
	global_load_lds_dwordx4 v[228:229], off
	s_add_i32 s0, 0, 0x18000
	s_add_i32 s1, 0, 0x1c000
	v_add_u32_e32 v140, s0, v223
	v_add_u32_e32 v156, s1, v223
	ds_read_b128 v[128:131], v140
	ds_read_b128 v[132:135], v140 offset:1024
	ds_read_b128 v[136:139], v140 offset:2048
	ds_read_b128 v[140:143], v140 offset:3072
	ds_read_b128 v[144:147], v156
	ds_read_b128 v[148:151], v156 offset:1024
	ds_read_b128 v[152:155], v156 offset:2048
	ds_read_b128 v[156:159], v156 offset:3072
	ds_read_b128 v[160:163], v226 offset:32768
	ds_read_b128 v[164:167], v226 offset:33792
	ds_read_b128 v[168:171], v226 offset:34816
	ds_read_b128 v[172:175], v226 offset:35840
	ds_read_b128 v[196:199], v226 offset:36864
	ds_read_b128 v[200:203], v226 offset:37888
	ds_read_b128 v[204:207], v226 offset:38912
	ds_read_b128 v[210:213], v226 offset:39936
	s_waitcnt vmcnt(8)
	s_waitcnt lgkmcnt(0)
	s_barrier
	s_setprio 1
	s_waitcnt lgkmcnt(0)
	v_mfma_f32_16x16x32_bf16 v[92:95], v[128:131], v[160:163], v[92:95]
	v_mfma_f32_16x16x32_bf16 v[44:47], v[136:139], v[160:163], v[44:47]
	v_mfma_f32_16x16x32_bf16 v[84:87], v[128:131], v[168:171], v[84:87]
	v_mfma_f32_16x16x32_bf16 v[36:39], v[136:139], v[168:171], v[36:39]
	v_mfma_f32_16x16x32_bf16 v[76:79], v[128:131], v[196:199], v[76:79]
	v_mfma_f32_16x16x32_bf16 v[28:31], v[136:139], v[196:199], v[28:31]
	v_mfma_f32_16x16x32_bf16 v[124:127], v[128:131], v[204:207], v[124:127]
	v_mfma_f32_16x16x32_bf16 v[120:123], v[136:139], v[204:207], v[120:123]
	v_mfma_f32_16x16x32_bf16 v[92:95], v[132:135], v[164:167], v[92:95]
	v_mfma_f32_16x16x32_bf16 v[44:47], v[140:143], v[164:167], v[44:47]
	v_mfma_f32_16x16x32_bf16 v[84:87], v[132:135], v[172:175], v[84:87]
	v_mfma_f32_16x16x32_bf16 v[36:39], v[140:143], v[172:175], v[36:39]
	v_mfma_f32_16x16x32_bf16 v[76:79], v[132:135], v[200:203], v[76:79]
	v_mfma_f32_16x16x32_bf16 v[28:31], v[140:143], v[200:203], v[28:31]
	v_mfma_f32_16x16x32_bf16 v[124:127], v[132:135], v[210:213], v[124:127]
	v_mfma_f32_16x16x32_bf16 v[120:123], v[140:143], v[210:213], v[120:123]
	s_setprio 0
	s_setprio 1
	v_mfma_f32_16x16x32_bf16 v[88:91], v[144:147], v[160:163], v[88:91]
	v_mfma_f32_16x16x32_bf16 v[40:43], v[152:155], v[160:163], v[40:43]
	v_mfma_f32_16x16x32_bf16 v[80:83], v[144:147], v[168:171], v[80:83]
	v_mfma_f32_16x16x32_bf16 v[32:35], v[152:155], v[168:171], v[32:35]
	v_mfma_f32_16x16x32_bf16 v[72:75], v[144:147], v[196:199], v[72:75]
	v_mfma_f32_16x16x32_bf16 v[24:27], v[152:155], v[196:199], v[24:27]
	v_mfma_f32_16x16x32_bf16 v[116:119], v[144:147], v[204:207], v[116:119]
	v_mfma_f32_16x16x32_bf16 v[112:115], v[152:155], v[204:207], v[112:115]
	v_mfma_f32_16x16x32_bf16 v[88:91], v[148:151], v[164:167], v[88:91]
	v_mfma_f32_16x16x32_bf16 v[40:43], v[156:159], v[164:167], v[40:43]
	v_mfma_f32_16x16x32_bf16 v[80:83], v[148:151], v[172:175], v[80:83]
	v_mfma_f32_16x16x32_bf16 v[32:35], v[156:159], v[172:175], v[32:35]
	v_mfma_f32_16x16x32_bf16 v[72:75], v[148:151], v[200:203], v[72:75]
	v_mfma_f32_16x16x32_bf16 v[24:27], v[156:159], v[200:203], v[24:27]
	v_mfma_f32_16x16x32_bf16 v[116:119], v[148:151], v[210:213], v[116:119]
	v_mfma_f32_16x16x32_bf16 v[112:115], v[156:159], v[210:213], v[112:115]
	s_setprio 0
	s_barrier
; #define PG8_STAGE(bufoff, gbase, voff) do { _Pragma("unroll") for (int _i = 0; _i < 2; ++_i) \
;         __builtin_amdgcn_global_load_lds((const unsigned*)((const char*)(gbase) + (voff)[_i]), (PG8_LAS unsigned*)(lds + (bufoff) + ldsw + _i * 8192), 16, 0, 0); } while (0)
; #define PG8_LDA(dst, b, h) do { _Pragma("unroll") for (int m = 0; m < 4; ++m) _Pragma("unroll") for (int k = 0; k < 2; ++k) dst[m][k] = *(const PG8_LAS bf16x8*)(lds + PG8_SA(b, h) + aoff + m * 2048 + k * 1024); } while (0)
; #define PG8_LDB(dst, b, h) do { _Pragma("unroll") for (int n = 0; n < 2; ++n) _Pragma("unroll") for (int k = 0; k < 2; ++k) dst[n][k] = *(const PG8_LAS bf16x8*)(lds + PG8_SB(b, h) + boff + n * 2048 + k * 1024); } while (0)
; #define PG8_MMA(ai, bj, At, Bt) do { __builtin_amdgcn_s_setprio(1); _Pragma("unroll") for (int m = 0; m < 4; ++m) _Pragma("unroll") for (int n = 0; n < 2; ++n) _Pragma("unroll") for (int k = 0; k < 2; ++k) \
;         acc[ai][bj][m][n] = __builtin_amdgcn_mfma_f32_16x16x32_bf16(Bt[n][k], At[m][k], acc[ai][bj][m][n], 0, 0, 0); __builtin_amdgcn_s_setprio(0); } while (0)
; #define PG8_WAIT_V(n) asm volatile("s_waitcnt vmcnt(" #n ")" ::: "memory")
; template <class Epi, class Sched, bool ALIGN_EPI = false, bool SP2 = false>
; __device__ __forceinline__ void gemm_phase(PG8_LAS unsigned char* lds, const Gemm g, const Sched& S, const Epi& E) {
;     ...
;             PG8_LDB(B0, 0, 0); PG8_LDB(B1, 0, 1); PG8_SCHED; PG8_LDA(At, 0, 0); PG8_STAGE(PG8_SA(1, 1), a1 + hstep, voffA);
;             PG8_WAIT_V(8); PG8_WAIT_L(0); PG8_BAR; PG8_MMA(0, 0, At, B0); PG8_MMA(0, 1, At, B1); PG8_BAR; PG8_SCHED;
;             PG8_LDA(At, 0, 1); PG8_STAGE(PG8_SB(0, 0), b2, voffB); PG8_STAGE(PG8_SB(0, 1), b2 + hstep, voffB); PG8_STAGE(PG8_SA(0, 0), a2, voffA);
;             PG8_WAIT_V(8); PG8_WAIT_L(0); PG8_BAR; PG8_MMA(1, 0, At, B0); PG8_MMA(1, 1, At, B1); PG8_BAR; PG8_SCHED;
;             PG8_LDB(B0, 1, 0); PG8_LDB(B1, 1, 1); PG8_SCHED; PG8_LDA(At, 1, 0); PG8_STAGE(PG8_SA(0, 1), a2 + hstep, voffA);
;             PG8_WAIT_V(8); PG8_WAIT_L(0); PG8_BAR; PG8_MMA(0, 0, At, B0); PG8_MMA(0, 1, At, B1); PG8_BAR; PG8_SCHED;
;             PG8_LDA(At, 1, 1); PG8_STAGE(PG8_SB(1, 0), b3, voffB); PG8_STAGE(PG8_SB(1, 1), b3 + hstep, voffB); PG8_STAGE(PG8_SA(1, 0), a3, voffA);
;             PG8_WAIT_V(8); PG8_WAIT_L(0); PG8_BAR; PG8_MMA(1, 0, At, B0); PG8_MMA(1, 1, At, B1); PG8_BAR; PG8_SCHED;
	s_add_i32 s0, s0, s75
	v_lshl_add_u64 v[214:215], v[214:215], 0, s[40:41]
	s_mov_b32 m0, s0
	s_nop 0
	global_load_lds_dwordx4 v[214:215], off
	s_add_i32 m0, s0, 0x2000
	s_add_u32 s12, s12, 0x40080
	v_lshl_add_u64 v[214:215], v[216:217], 0, s[40:41]
	s_addc_u32 s13, s13, 0
	s_add_i32 s0, s1, s75
	global_load_lds_dwordx4 v[214:215], off
	v_lshl_add_u64 v[214:215], s[12:13], 0, v[178:179]
	s_mov_b32 m0, s0
	s_nop 0
	global_load_lds_dwordx4 v[214:215], off
	v_lshl_add_u64 v[214:215], s[12:13], 0, v[182:183]
	s_add_i32 m0, s0, 0x2000
	s_nop 0
	global_load_lds_dwordx4 v[214:215], off
	v_lshl_add_u64 v[214:215], v[218:219], 0, s[40:41]
	s_mov_b32 m0, s85
	s_nop 0
	global_load_lds_dwordx4 v[214:215], off
	v_lshl_add_u64 v[214:215], v[220:221], 0, s[40:41]
	s_mov_b32 m0, s86
	s_nop 0
	global_load_lds_dwordx4 v[214:215], off
	ds_read_b128 v[160:163], v226 offset:49152
	ds_read_b128 v[164:167], v226 offset:50176
	ds_read_b128 v[168:171], v226 offset:51200
	ds_read_b128 v[172:175], v226 offset:52224
	ds_read_b128 v[196:199], v226 offset:53248
	ds_read_b128 v[200:203], v226 offset:54272
	ds_read_b128 v[204:207], v226 offset:55296
	ds_read_b128 v[210:213], v226 offset:56320
	s_waitcnt vmcnt(8)
	s_waitcnt lgkmcnt(0)
	s_barrier
	s_setprio 1
	s_waitcnt lgkmcnt(0)
	v_mfma_f32_16x16x32_bf16 v[68:71], v[128:131], v[160:163], v[68:71]
	v_mfma_f32_16x16x32_bf16 v[20:23], v[136:139], v[160:163], v[20:23]
	v_mfma_f32_16x16x32_bf16 v[60:63], v[128:131], v[168:171], v[60:63]
	v_mfma_f32_16x16x32_bf16 v[12:15], v[136:139], v[168:171], v[12:15]
	v_mfma_f32_16x16x32_bf16 v[52:55], v[128:131], v[196:199], v[52:55]
	v_mfma_f32_16x16x32_bf16 v[4:7], v[136:139], v[196:199], v[4:7]
	v_mfma_f32_16x16x32_bf16 v[108:111], v[128:131], v[204:207], v[108:111]
	v_mfma_f32_16x16x32_bf16 v[104:107], v[136:139], v[204:207], v[104:107]
	v_mfma_f32_16x16x32_bf16 v[68:71], v[132:135], v[164:167], v[68:71]
	v_mfma_f32_16x16x32_bf16 v[20:23], v[140:143], v[164:167], v[20:23]
	v_mfma_f32_16x16x32_bf16 v[60:63], v[132:135], v[172:175], v[60:63]
	v_mfma_f32_16x16x32_bf16 v[12:15], v[140:143], v[172:175], v[12:15]
	v_mfma_f32_16x16x32_bf16 v[52:55], v[132:135], v[200:203], v[52:55]
	v_mfma_f32_16x16x32_bf16 v[4:7], v[140:143], v[200:203], v[4:7]
	v_mfma_f32_16x16x32_bf16 v[108:111], v[132:135], v[210:213], v[108:111]
	v_mfma_f32_16x16x32_bf16 v[104:107], v[140:143], v[210:213], v[104:107]
	s_setprio 0
	s_setprio 1
	v_mfma_f32_16x16x32_bf16 v[64:67], v[144:147], v[160:163], v[64:67]
	v_mfma_f32_16x16x32_bf16 v[16:19], v[152:155], v[160:163], v[16:19]
	v_mfma_f32_16x16x32_bf16 v[56:59], v[144:147], v[168:171], v[56:59]
	v_mfma_f32_16x16x32_bf16 v[8:11], v[152:155], v[168:171], v[8:11]
	v_mfma_f32_16x16x32_bf16 v[48:51], v[144:147], v[196:199], v[48:51]
	v_mfma_f32_16x16x32_bf16 v[0:3], v[152:155], v[196:199], v[0:3]
	v_mfma_f32_16x16x32_bf16 v[100:103], v[144:147], v[204:207], v[100:103]
	v_mfma_f32_16x16x32_bf16 v[96:99], v[152:155], v[204:207], v[96:99]
	v_mfma_f32_16x16x32_bf16 v[64:67], v[148:151], v[164:167], v[64:67]
	v_mfma_f32_16x16x32_bf16 v[16:19], v[156:159], v[164:167], v[16:19]
	v_mfma_f32_16x16x32_bf16 v[56:59], v[148:151], v[172:175], v[56:59]
	v_mfma_f32_16x16x32_bf16 v[8:11], v[156:159], v[172:175], v[8:11]
	v_mfma_f32_16x16x32_bf16 v[48:51], v[148:151], v[200:203], v[48:51]
	v_mfma_f32_16x16x32_bf16 v[0:3], v[156:159], v[200:203], v[0:3]
	v_mfma_f32_16x16x32_bf16 v[100:103], v[148:151], v[210:213], v[100:103]
	v_mfma_f32_16x16x32_bf16 v[96:99], v[156:159], v[210:213], v[96:99]
	s_setprio 0
	s_barrier
	s_add_i32 s21, s21, 2
	s_add_u32 s10, s10, 0x100
	s_addc_u32 s11, s11, 0
	s_add_u32 s19, s19, 0x100
	s_addc_u32 s20, s20, 0
	s_cmp_gt_u32 s21, 13
	s_cbranch_scc0 .LBB0_574
	s_and_b64 vcc, exec, s[42:43]
	s_cbranch_vccnz .LBB0_579
	s_cmp_lg_u32 s18, 64
	s_mov_b64 s[10:11], -1
	s_cbranch_scc1 .LBB0_580

; #define PG8_STAGE(bufoff, gbase, voff) do { _Pragma("unroll") for (int _i = 0; _i < 2; ++_i) \
;         __builtin_amdgcn_global_load_lds((const unsigned*)((const char*)(gbase) + (voff)[_i]), (PG8_LAS unsigned*)(lds + (bufoff) + ldsw + _i * 8192), 16, 0, 0); } while (0)
; #define PG8_LDA(dst, b, h) do { _Pragma("unroll") for (int m = 0; m < 4; ++m) _Pragma("unroll") for (int k = 0; k < 2; ++k) dst[m][k] = *(const PG8_LAS bf16x8*)(lds + PG8_SA(b, h) + aoff + m * 2048 + k * 1024); } while (0)
; #define PG8_LDB(dst, b, h) do { _Pragma("unroll") for (int n = 0; n < 2; ++n) _Pragma("unroll") for (int k = 0; k < 2; ++k) dst[n][k] = *(const PG8_LAS bf16x8*)(lds + PG8_SB(b, h) + boff + n * 2048 + k * 1024); } while (0)
; #define PG8_MMA(ai, bj, At, Bt) do { __builtin_amdgcn_s_setprio(1); _Pragma("unroll") for (int m = 0; m < 4; ++m) _Pragma("unroll") for (int n = 0; n < 2; ++n) _Pragma("unroll") for (int k = 0; k < 2; ++k) \
;         acc[ai][bj][m][n] = __builtin_amdgcn_mfma_f32_16x16x32_bf16(Bt[n][k], At[m][k], acc[ai][bj][m][n], 0, 0, 0); __builtin_amdgcn_s_setprio(0); } while (0)
; #define PG8_WAIT_V(n) asm volatile("s_waitcnt vmcnt(" #n ")" ::: "memory")
; #define PG8_WAIT_L(n) asm volatile("s_waitcnt lgkmcnt(" #n ")" ::: "memory")
; #define PG8_BAR __builtin_amdgcn_s_barrier()
; #define PG8_SCHED __builtin_amdgcn_sched_barrier(0)
; template <class Epi, class Sched, bool ALIGN_EPI = false, bool SP2 = false>
; __device__ __forceinline__ void gemm_phase(PG8_LAS unsigned char* lds, const Gemm g, const Sched& S, const Epi& E) {
;     ...
;             PG8_LDB(B0, 0, 0); PG8_LDB(B1, 0, 1); PG8_SCHED; PG8_LDA(At, 0, 0); PG8_STAGE(PG8_SA(1, 1), a1 + hstep, voffA);
;             PG8_WAIT_V(8); PG8_WAIT_L(0); PG8_BAR; PG8_MMA(0, 0, At, B0); PG8_MMA(0, 1, At, B1); PG8_BAR; PG8_SCHED;
;             PG8_LDA(At, 0, 1); PG8_STAGE(PG8_SB(0, 0), b2, voffB); PG8_STAGE(PG8_SB(0, 1), b2 + hstep, voffB); PG8_STAGE(PG8_SA(0, 0), a2, voffA);
;             PG8_WAIT_V(8); PG8_WAIT_L(0); PG8_BAR; PG8_MMA(1, 0, At, B0); PG8_MMA(1, 1, At, B1); PG8_BAR; PG8_SCHED;
.LBB0_674:
	s_add_u32 s24, s22, 0xfff50080
	s_addc_u32 s25, s23, -1
	s_cmp_eq_u32 s52, 40
	s_cselect_b32 s29, s5, s25
	s_cselect_b32 s28, s4, s24
	s_cselect_b32 s25, s21, s51
	s_cselect_b32 s24, s20, s50
	v_lshl_add_u64 v[166:167], s[22:23], 0, v[154:155]
	s_add_i32 m0, s35, 0xc000
	s_nop 0
	global_load_lds_dwordx4 v[166:167], off
	v_lshl_add_u64 v[166:167], s[22:23], 0, v[156:157]
	s_add_i32 m0, s35, 0xe000
	s_nop 0
	global_load_lds_dwordx4 v[166:167], off
	ds_read_b128 v[128:131], v171
	ds_read_b128 v[132:135], v171 offset:1024
	ds_read_b128 v[136:139], v171 offset:2048
	ds_read_b128 v[140:143], v171 offset:3072
	ds_read_b128 v[162:165], v172
	ds_read_b128 v[174:177], v172 offset:1024
	ds_read_b128 v[178:181], v172 offset:2048
	ds_read_b128 v[182:185], v172 offset:3072
	ds_read_b128 v[186:189], v173
	ds_read_b128 v[190:193], v173 offset:1024
	ds_read_b128 v[194:197], v173 offset:2048
	ds_read_b128 v[198:201], v173 offset:3072
	ds_read_b128 v[202:205], v173 offset:4096
	ds_read_b128 v[206:209], v173 offset:5120
	ds_read_b128 v[210:213], v173 offset:6144
	ds_read_b128 v[214:217], v173 offset:7168
	s_waitcnt vmcnt(8)
	s_waitcnt lgkmcnt(0)
	s_barrier
	s_setprio 1
	s_waitcnt lgkmcnt(0)
	v_mfma_f32_16x16x32_bf16 v[124:127], v[128:131], v[186:189], v[124:127]
	v_mfma_f32_16x16x32_bf16 v[120:123], v[136:139], v[186:189], v[120:123]
	v_mfma_f32_16x16x32_bf16 v[116:119], v[128:131], v[194:197], v[116:119]
	v_mfma_f32_16x16x32_bf16 v[112:115], v[136:139], v[194:197], v[112:115]
	v_mfma_f32_16x16x32_bf16 v[96:99], v[128:131], v[202:205], v[96:99]
	v_mfma_f32_16x16x32_bf16 v[88:91], v[136:139], v[202:205], v[88:91]
	v_mfma_f32_16x16x32_bf16 v[80:83], v[128:131], v[210:213], v[80:83]
	v_mfma_f32_16x16x32_bf16 v[72:75], v[136:139], v[210:213], v[72:75]
	v_mfma_f32_16x16x32_bf16 v[124:127], v[132:135], v[190:193], v[124:127]
	v_mfma_f32_16x16x32_bf16 v[120:123], v[140:143], v[190:193], v[120:123]
	v_mfma_f32_16x16x32_bf16 v[116:119], v[132:135], v[198:201], v[116:119]
	v_mfma_f32_16x16x32_bf16 v[112:115], v[140:143], v[198:201], v[112:115]
	v_mfma_f32_16x16x32_bf16 v[96:99], v[132:135], v[206:209], v[96:99]
	v_mfma_f32_16x16x32_bf16 v[88:91], v[140:143], v[206:209], v[88:91]
	v_mfma_f32_16x16x32_bf16 v[80:83], v[132:135], v[214:217], v[80:83]
	v_mfma_f32_16x16x32_bf16 v[72:75], v[140:143], v[214:217], v[72:75]
	s_setprio 0
	s_setprio 1
	v_mfma_f32_16x16x32_bf16 v[108:111], v[162:165], v[186:189], v[108:111]
	v_mfma_f32_16x16x32_bf16 v[104:107], v[178:181], v[186:189], v[104:107]
	v_mfma_f32_16x16x32_bf16 v[100:103], v[162:165], v[194:197], v[100:103]
	v_mfma_f32_16x16x32_bf16 v[92:95], v[178:181], v[194:197], v[92:95]
	v_mfma_f32_16x16x32_bf16 v[84:87], v[162:165], v[202:205], v[84:87]
	v_mfma_f32_16x16x32_bf16 v[76:79], v[178:181], v[202:205], v[76:79]
	v_mfma_f32_16x16x32_bf16 v[68:71], v[162:165], v[210:213], v[68:71]
	v_mfma_f32_16x16x32_bf16 v[64:67], v[178:181], v[210:213], v[64:67]
	v_mfma_f32_16x16x32_bf16 v[108:111], v[174:177], v[190:193], v[108:111]
	v_mfma_f32_16x16x32_bf16 v[104:107], v[182:185], v[190:193], v[104:107]
	v_mfma_f32_16x16x32_bf16 v[100:103], v[174:177], v[198:201], v[100:103]
	v_mfma_f32_16x16x32_bf16 v[92:95], v[182:185], v[198:201], v[92:95]
	v_mfma_f32_16x16x32_bf16 v[84:87], v[174:177], v[206:209], v[84:87]
	v_mfma_f32_16x16x32_bf16 v[76:79], v[182:185], v[206:209], v[76:79]
	v_mfma_f32_16x16x32_bf16 v[68:71], v[174:177], v[214:217], v[68:71]
	v_mfma_f32_16x16x32_bf16 v[64:67], v[182:185], v[214:217], v[64:67]
	s_setprio 0
	s_barrier
	s_add_i32 s53, s43, s34
	v_lshl_add_u64 v[166:167], s[24:25], 0, v[146:147]
	s_mov_b32 m0, s53
	s_nop 0
	global_load_lds_dwordx4 v[166:167], off
	s_add_i32 m0, s53, 0x2000
	s_add_u32 s54, s24, 0xb0000
	v_lshl_add_u64 v[218:219], s[24:25], 0, v[150:151]
	s_addc_u32 s55, s25, 0
	s_add_i32 s53, s44, s34
	global_load_lds_dwordx4 v[218:219], off
	v_lshl_add_u64 v[220:221], s[54:55], 0, v[146:147]
	s_mov_b32 m0, s53
	v_lshl_add_u64 v[222:223], s[28:29], 0, v[148:149]
	global_load_lds_dwordx4 v[220:221], off
	v_lshl_add_u64 v[220:221], s[54:55], 0, v[150:151]
	s_add_i32 m0, s53, 0x2000
	s_nop 0
	global_load_lds_dwordx4 v[220:221], off
	v_lshl_add_u64 v[220:221], s[28:29], 0, v[144:145]
	s_mov_b32 m0, s35
	s_nop 0
	global_load_lds_dwordx4 v[220:221], off
	s_mov_b32 m0, s36
	s_nop 0
	global_load_lds_dwordx4 v[222:223], off
	ds_read_b128 v[186:189], v173 offset:16384
	ds_read_b128 v[190:193], v173 offset:17408
	ds_read_b128 v[194:197], v173 offset:18432
	ds_read_b128 v[198:201], v173 offset:19456
	ds_read_b128 v[202:205], v173 offset:20480
	ds_read_b128 v[206:209], v173 offset:21504
	ds_read_b128 v[210:213], v173 offset:22528
	ds_read_b128 v[214:217], v173 offset:23552
	s_waitcnt vmcnt(8)
	s_waitcnt lgkmcnt(0)
	s_barrier
; #define PG8_STAGE(bufoff, gbase, voff) do { _Pragma("unroll") for (int _i = 0; _i < 2; ++_i) \
;         __builtin_amdgcn_global_load_lds((const unsigned*)((const char*)(gbase) + (voff)[_i]), (PG8_LAS unsigned*)(lds + (bufoff) + ldsw + _i * 8192), 16, 0, 0); } while (0)
; #define PG8_LDA(dst, b, h) do { _Pragma("unroll") for (int m = 0; m < 4; ++m) _Pragma("unroll") for (int k = 0; k < 2; ++k) dst[m][k] = *(const PG8_LAS bf16x8*)(lds + PG8_SA(b, h) + aoff + m * 2048 + k * 1024); } while (0)
; #define PG8_LDB(dst, b, h) do { _Pragma("unroll") for (int n = 0; n < 2; ++n) _Pragma("unroll") for (int k = 0; k < 2; ++k) dst[n][k] = *(const PG8_LAS bf16x8*)(lds + PG8_SB(b, h) + boff + n * 2048 + k * 1024); } while (0)
; #define PG8_MMA(ai, bj, At, Bt) do { __builtin_amdgcn_s_setprio(1); _Pragma("unroll") for (int m = 0; m < 4; ++m) _Pragma("unroll") for (int n = 0; n < 2; ++n) _Pragma("unroll") for (int k = 0; k < 2; ++k) \
;         acc[ai][bj][m][n] = __builtin_amdgcn_mfma_f32_16x16x32_bf16(Bt[n][k], At[m][k], acc[ai][bj][m][n], 0, 0, 0); __builtin_amdgcn_s_setprio(0); } while (0)
; #define PG8_WAIT_V(n) asm volatile("s_waitcnt vmcnt(" #n ")" ::: "memory")
; #define PG8_WAIT_L(n) asm volatile("s_waitcnt lgkmcnt(" #n ")" ::: "memory")
; #define PG8_BAR __builtin_amdgcn_s_barrier()
; #define PG8_SCHED __builtin_amdgcn_sched_barrier(0)
; template <class Epi, class Sched, bool ALIGN_EPI = false, bool SP2 = false>
; __device__ __forceinline__ void gemm_phase(PG8_LAS unsigned char* lds, const Gemm g, const Sched& S, const Epi& E) {
;     ...
;             PG8_WAIT_V(8); PG8_WAIT_L(0); PG8_BAR; PG8_MMA(1, 0, At, B0); PG8_MMA(1, 1, At, B1); PG8_BAR; PG8_SCHED;
;             PG8_LDB(B0, 1, 0); PG8_LDB(B1, 1, 1); PG8_SCHED; PG8_LDA(At, 1, 0); PG8_STAGE(PG8_SA(0, 1), a2 + hstep, voffA);
;             PG8_WAIT_V(8); PG8_WAIT_L(0); PG8_BAR; PG8_MMA(0, 0, At, B0); PG8_MMA(0, 1, At, B1); PG8_BAR; PG8_SCHED;
	s_setprio 1
	s_waitcnt lgkmcnt(0)
	v_mfma_f32_16x16x32_bf16 v[60:63], v[128:131], v[186:189], v[60:63]
	v_mfma_f32_16x16x32_bf16 v[56:59], v[136:139], v[186:189], v[56:59]
	v_mfma_f32_16x16x32_bf16 v[48:51], v[128:131], v[194:197], v[48:51]
	v_mfma_f32_16x16x32_bf16 v[40:43], v[136:139], v[194:197], v[40:43]
	v_mfma_f32_16x16x32_bf16 v[32:35], v[128:131], v[202:205], v[32:35]
	v_mfma_f32_16x16x32_bf16 v[24:27], v[136:139], v[202:205], v[24:27]
	v_mfma_f32_16x16x32_bf16 v[16:19], v[128:131], v[210:213], v[16:19]
	v_mfma_f32_16x16x32_bf16 v[8:11], v[136:139], v[210:213], v[8:11]
	v_mfma_f32_16x16x32_bf16 v[60:63], v[132:135], v[190:193], v[60:63]
	v_mfma_f32_16x16x32_bf16 v[56:59], v[140:143], v[190:193], v[56:59]
	v_mfma_f32_16x16x32_bf16 v[48:51], v[132:135], v[198:201], v[48:51]
	v_mfma_f32_16x16x32_bf16 v[40:43], v[140:143], v[198:201], v[40:43]
	v_mfma_f32_16x16x32_bf16 v[32:35], v[132:135], v[206:209], v[32:35]
	v_mfma_f32_16x16x32_bf16 v[24:27], v[140:143], v[206:209], v[24:27]
	v_mfma_f32_16x16x32_bf16 v[16:19], v[132:135], v[214:217], v[16:19]
	v_mfma_f32_16x16x32_bf16 v[8:11], v[140:143], v[214:217], v[8:11]
	s_setprio 0
	s_setprio 1
	v_mfma_f32_16x16x32_bf16 v[52:55], v[162:165], v[186:189], v[52:55]
	v_mfma_f32_16x16x32_bf16 v[44:47], v[178:181], v[186:189], v[44:47]
	v_mfma_f32_16x16x32_bf16 v[36:39], v[162:165], v[194:197], v[36:39]
	v_mfma_f32_16x16x32_bf16 v[28:31], v[178:181], v[194:197], v[28:31]
	v_mfma_f32_16x16x32_bf16 v[20:23], v[162:165], v[202:205], v[20:23]
	v_mfma_f32_16x16x32_bf16 v[12:15], v[178:181], v[202:205], v[12:15]
	v_mfma_f32_16x16x32_bf16 v[4:7], v[162:165], v[210:213], v[4:7]
	v_mfma_f32_16x16x32_bf16 v[0:3], v[178:181], v[210:213], v[0:3]
	v_mfma_f32_16x16x32_bf16 v[52:55], v[174:177], v[190:193], v[52:55]
	v_mfma_f32_16x16x32_bf16 v[44:47], v[182:185], v[190:193], v[44:47]
	v_mfma_f32_16x16x32_bf16 v[36:39], v[174:177], v[198:201], v[36:39]
	v_mfma_f32_16x16x32_bf16 v[28:31], v[182:185], v[198:201], v[28:31]
	v_mfma_f32_16x16x32_bf16 v[20:23], v[174:177], v[206:209], v[20:23]
	v_mfma_f32_16x16x32_bf16 v[12:15], v[182:185], v[206:209], v[12:15]
	v_mfma_f32_16x16x32_bf16 v[4:7], v[174:177], v[214:217], v[4:7]
	v_mfma_f32_16x16x32_bf16 v[0:3], v[182:185], v[214:217], v[0:3]
	s_setprio 0
	s_barrier
	s_add_u32 s28, s28, 0xb0000
	s_addc_u32 s29, s29, 0
	s_mov_b32 m0, s37
	v_lshl_add_u64 v[224:225], s[28:29], 0, v[144:145]
	global_load_lds_dwordx4 v[224:225], off
	v_lshl_add_u64 v[224:225], s[28:29], 0, v[148:149]
	s_mov_b32 m0, s38
	s_nop 0
	global_load_lds_dwordx4 v[224:225], off
	s_add_i32 s53, 0, 0x18000
	s_add_i32 s54, 0, 0x1c000
	v_add_u32_e32 v140, s53, v168
	v_add_u32_e32 v152, s54, v168
	ds_read_b128 v[128:131], v140
	ds_read_b128 v[132:135], v140 offset:1024
	ds_read_b128 v[136:139], v140 offset:2048
	ds_read_b128 v[140:143], v140 offset:3072
	ds_read_b128 v[162:165], v152
	ds_read_b128 v[174:177], v152 offset:1024
	ds_read_b128 v[178:181], v152 offset:2048
	ds_read_b128 v[182:185], v152 offset:3072
	ds_read_b128 v[186:189], v173 offset:32768
	ds_read_b128 v[190:193], v173 offset:33792
	ds_read_b128 v[194:197], v173 offset:34816
	ds_read_b128 v[198:201], v173 offset:35840
	ds_read_b128 v[202:205], v173 offset:36864
	ds_read_b128 v[206:209], v173 offset:37888
	ds_read_b128 v[210:213], v173 offset:38912
	ds_read_b128 v[214:217], v173 offset:39936
	s_waitcnt vmcnt(8)
	s_waitcnt lgkmcnt(0)
	s_barrier
	s_setprio 1
	s_waitcnt lgkmcnt(0)
	v_mfma_f32_16x16x32_bf16 v[124:127], v[128:131], v[186:189], v[124:127]
	v_mfma_f32_16x16x32_bf16 v[120:123], v[136:139], v[186:189], v[120:123]
	v_mfma_f32_16x16x32_bf16 v[116:119], v[128:131], v[194:197], v[116:119]
	v_mfma_f32_16x16x32_bf16 v[112:115], v[136:139], v[194:197], v[112:115]
	v_mfma_f32_16x16x32_bf16 v[96:99], v[128:131], v[202:205], v[96:99]
	v_mfma_f32_16x16x32_bf16 v[88:91], v[136:139], v[202:205], v[88:91]
	v_mfma_f32_16x16x32_bf16 v[80:83], v[128:131], v[210:213], v[80:83]
	v_mfma_f32_16x16x32_bf16 v[72:75], v[136:139], v[210:213], v[72:75]
	v_mfma_f32_16x16x32_bf16 v[124:127], v[132:135], v[190:193], v[124:127]
	v_mfma_f32_16x16x32_bf16 v[120:123], v[140:143], v[190:193], v[120:123]
	v_mfma_f32_16x16x32_bf16 v[116:119], v[132:135], v[198:201], v[116:119]
	v_mfma_f32_16x16x32_bf16 v[112:115], v[140:143], v[198:201], v[112:115]
	v_mfma_f32_16x16x32_bf16 v[96:99], v[132:135], v[206:209], v[96:99]
	v_mfma_f32_16x16x32_bf16 v[88:91], v[140:143], v[206:209], v[88:91]
	v_mfma_f32_16x16x32_bf16 v[80:83], v[132:135], v[214:217], v[80:83]
	v_mfma_f32_16x16x32_bf16 v[72:75], v[140:143], v[214:217], v[72:75]
	s_setprio 0
	s_setprio 1
	v_mfma_f32_16x16x32_bf16 v[108:111], v[162:165], v[186:189], v[108:111]
	v_mfma_f32_16x16x32_bf16 v[104:107], v[178:181], v[186:189], v[104:107]
	v_mfma_f32_16x16x32_bf16 v[100:103], v[162:165], v[194:197], v[100:103]
	v_mfma_f32_16x16x32_bf16 v[92:95], v[178:181], v[194:197], v[92:95]
	v_mfma_f32_16x16x32_bf16 v[84:87], v[162:165], v[202:205], v[84:87]
	v_mfma_f32_16x16x32_bf16 v[76:79], v[178:181], v[202:205], v[76:79]
	v_mfma_f32_16x16x32_bf16 v[68:71], v[162:165], v[210:213], v[68:71]
	v_mfma_f32_16x16x32_bf16 v[64:67], v[178:181], v[210:213], v[64:67]
	v_mfma_f32_16x16x32_bf16 v[108:111], v[174:177], v[190:193], v[108:111]
	v_mfma_f32_16x16x32_bf16 v[104:107], v[182:185], v[190:193], v[104:107]
	v_mfma_f32_16x16x32_bf16 v[100:103], v[174:177], v[198:201], v[100:103]
	v_mfma_f32_16x16x32_bf16 v[92:95], v[182:185], v[198:201], v[92:95]
	v_mfma_f32_16x16x32_bf16 v[84:87], v[174:177], v[206:209], v[84:87]
	v_mfma_f32_16x16x32_bf16 v[76:79], v[182:185], v[206:209], v[76:79]
	v_mfma_f32_16x16x32_bf16 v[68:71], v[174:177], v[214:217], v[68:71]
	v_mfma_f32_16x16x32_bf16 v[64:67], v[182:185], v[214:217], v[64:67]
	s_setprio 0
	s_barrier
; #define PG8_STAGE(bufoff, gbase, voff) do { _Pragma("unroll") for (int _i = 0; _i < 2; ++_i) \
;         __builtin_amdgcn_global_load_lds((const unsigned*)((const char*)(gbase) + (voff)[_i]), (PG8_LAS unsigned*)(lds + (bufoff) + ldsw + _i * 8192), 16, 0, 0); } while (0)
; #define PG8_LDA(dst, b, h) do { _Pragma("unroll") for (int m = 0; m < 4; ++m) _Pragma("unroll") for (int k = 0; k < 2; ++k) dst[m][k] = *(const PG8_LAS bf16x8*)(lds + PG8_SA(b, h) + aoff + m * 2048 + k * 1024); } while (0)
; #define PG8_MMA(ai, bj, At, Bt) do { __builtin_amdgcn_s_setprio(1); _Pragma("unroll") for (int m = 0; m < 4; ++m) _Pragma("unroll") for (int n = 0; n < 2; ++n) _Pragma("unroll") for (int k = 0; k < 2; ++k) \
;         acc[ai][bj][m][n] = __builtin_amdgcn_mfma_f32_16x16x32_bf16(Bt[n][k], At[m][k], acc[ai][bj][m][n], 0, 0, 0); __builtin_amdgcn_s_setprio(0); } while (0)
; #define PG8_WAIT_V(n) asm volatile("s_waitcnt vmcnt(" #n ")" ::: "memory")
; #define PG8_WAIT_L(n) asm volatile("s_waitcnt lgkmcnt(" #n ")" ::: "memory")
; #define PG8_BAR __builtin_amdgcn_s_barrier()
; #define PG8_SCHED __builtin_amdgcn_sched_barrier(0)
; template <class Epi, class Sched, bool ALIGN_EPI = false, bool SP2 = false>
; __device__ __forceinline__ void gemm_phase(PG8_LAS unsigned char* lds, const Gemm g, const Sched& S, const Epi& E) {
;     ...
;             PG8_LDA(At, 1, 1); PG8_STAGE(PG8_SB(1, 0), b3, voffB); PG8_STAGE(PG8_SB(1, 1), b3 + hstep, voffB); PG8_STAGE(PG8_SA(1, 0), a3, voffA);
;             PG8_WAIT_V(8); PG8_WAIT_L(0); PG8_BAR; PG8_MMA(1, 0, At, B0); PG8_MMA(1, 1, At, B1); PG8_BAR; PG8_SCHED;
	s_add_i32 s28, s53, s34
	v_lshl_add_u64 v[166:167], v[166:167], 0, s[14:15]
	s_mov_b32 m0, s28
	s_nop 0
	global_load_lds_dwordx4 v[166:167], off
	s_add_i32 m0, s28, 0x2000
	s_add_u32 s24, s24, 0xb0080
	v_lshl_add_u64 v[166:167], v[218:219], 0, s[14:15]
	s_addc_u32 s25, s25, 0
	s_add_i32 s28, s54, s34
	global_load_lds_dwordx4 v[166:167], off
	v_lshl_add_u64 v[166:167], s[24:25], 0, v[146:147]
	s_mov_b32 m0, s28
	s_nop 0
	global_load_lds_dwordx4 v[166:167], off
	v_lshl_add_u64 v[166:167], s[24:25], 0, v[150:151]
	s_add_i32 m0, s28, 0x2000
	s_nop 0
	global_load_lds_dwordx4 v[166:167], off
	v_lshl_add_u64 v[166:167], v[220:221], 0, s[14:15]
	s_mov_b32 m0, s40
	s_nop 0
	global_load_lds_dwordx4 v[166:167], off
	v_lshl_add_u64 v[166:167], v[222:223], 0, s[14:15]
	s_mov_b32 m0, s41
	s_nop 0
	global_load_lds_dwordx4 v[166:167], off
	ds_read_b128 v[186:189], v173 offset:49152
	ds_read_b128 v[190:193], v173 offset:50176
	ds_read_b128 v[194:197], v173 offset:51200
	ds_read_b128 v[198:201], v173 offset:52224
	ds_read_b128 v[202:205], v173 offset:53248
	ds_read_b128 v[206:209], v173 offset:54272
	ds_read_b128 v[210:213], v173 offset:55296
	ds_read_b128 v[214:217], v173 offset:56320
	s_waitcnt vmcnt(8)
	s_waitcnt lgkmcnt(0)
	s_barrier
	s_setprio 1
	s_waitcnt lgkmcnt(0)
	v_mfma_f32_16x16x32_bf16 v[60:63], v[128:131], v[186:189], v[60:63]
	v_mfma_f32_16x16x32_bf16 v[56:59], v[136:139], v[186:189], v[56:59]
	v_mfma_f32_16x16x32_bf16 v[48:51], v[128:131], v[194:197], v[48:51]
	v_mfma_f32_16x16x32_bf16 v[40:43], v[136:139], v[194:197], v[40:43]
	v_mfma_f32_16x16x32_bf16 v[32:35], v[128:131], v[202:205], v[32:35]
	v_mfma_f32_16x16x32_bf16 v[24:27], v[136:139], v[202:205], v[24:27]
	v_mfma_f32_16x16x32_bf16 v[16:19], v[128:131], v[210:213], v[16:19]
	v_mfma_f32_16x16x32_bf16 v[8:11], v[136:139], v[210:213], v[8:11]
	v_mfma_f32_16x16x32_bf16 v[60:63], v[132:135], v[190:193], v[60:63]
	v_mfma_f32_16x16x32_bf16 v[56:59], v[140:143], v[190:193], v[56:59]
	v_mfma_f32_16x16x32_bf16 v[48:51], v[132:135], v[198:201], v[48:51]
	v_mfma_f32_16x16x32_bf16 v[40:43], v[140:143], v[198:201], v[40:43]
	v_mfma_f32_16x16x32_bf16 v[32:35], v[132:135], v[206:209], v[32:35]
	v_mfma_f32_16x16x32_bf16 v[24:27], v[140:143], v[206:209], v[24:27]
	v_mfma_f32_16x16x32_bf16 v[16:19], v[132:135], v[214:217], v[16:19]
	v_mfma_f32_16x16x32_bf16 v[8:11], v[140:143], v[214:217], v[8:11]
	s_setprio 0
	s_setprio 1
	v_mfma_f32_16x16x32_bf16 v[52:55], v[162:165], v[186:189], v[52:55]
	v_mfma_f32_16x16x32_bf16 v[44:47], v[178:181], v[186:189], v[44:47]
	v_mfma_f32_16x16x32_bf16 v[36:39], v[162:165], v[194:197], v[36:39]
	v_mfma_f32_16x16x32_bf16 v[28:31], v[178:181], v[194:197], v[28:31]
	v_mfma_f32_16x16x32_bf16 v[20:23], v[162:165], v[202:205], v[20:23]
	v_mfma_f32_16x16x32_bf16 v[12:15], v[178:181], v[202:205], v[12:15]
	v_mfma_f32_16x16x32_bf16 v[4:7], v[162:165], v[210:213], v[4:7]
	v_mfma_f32_16x16x32_bf16 v[0:3], v[178:181], v[210:213], v[0:3]
	v_mfma_f32_16x16x32_bf16 v[52:55], v[174:177], v[190:193], v[52:55]
	v_mfma_f32_16x16x32_bf16 v[44:47], v[182:185], v[190:193], v[44:47]
	v_mfma_f32_16x16x32_bf16 v[36:39], v[174:177], v[198:201], v[36:39]
	v_mfma_f32_16x16x32_bf16 v[28:31], v[182:185], v[198:201], v[28:31]
	v_mfma_f32_16x16x32_bf16 v[20:23], v[174:177], v[206:209], v[20:23]
	v_mfma_f32_16x16x32_bf16 v[12:15], v[182:185], v[206:209], v[12:15]
	v_mfma_f32_16x16x32_bf16 v[4:7], v[174:177], v[214:217], v[4:7]
	v_mfma_f32_16x16x32_bf16 v[0:3], v[182:185], v[214:217], v[0:3]
	s_setprio 0
	s_barrier
	s_add_i32 s52, s52, 2
	s_add_u32 s22, s22, 0x100
	s_addc_u32 s23, s23, 0
	s_add_u32 s50, s50, 0x100
	s_addc_u32 s51, s51, 0
	s_cmp_gt_u32 s52, 41
	s_cbranch_scc0 .LBB0_674
	s_and_b64 vcc, exec, s[16:17]
	s_cbranch_vccz .LBB0_677
	s_barrier
